# v50 + norm_rows row reductions: ds_swizzle SWAP 1/2/4/8 steps replaced by DPP adds (quad_perm / row_half_mirror / row_mirror), bitwise-identical sums
# baseline (speedup 1.0000x reference)
.LBB0_805:
	v_readlane_b32 s16, v252, 0
	v_readlane_b32 s18, v252, 2
	v_mov_b32_e32 v66, v202
	v_readlane_b32 s19, v252, 3
	s_add_u32 s0, s18, s2
	s_addc_u32 s1, s19, s3
	v_ashrrev_i32_e32 v67, 31, v66
	v_lshl_add_u64 v[72:73], v[66:67], 3, s[0:1]
	v_add_co_u32_e32 v70, vcc, 0x44700000, v72
	v_readlane_b32 s17, v252, 1
	s_nop 0
	v_addc_co_u32_e32 v71, vcc, 0, v73, vcc
	v_add_co_u32_e32 v68, vcc, 0x44701000, v72
	global_load_dwordx2 v[74:75], v[70:71], off
	global_load_dwordx2 v[76:77], v[70:71], off offset:512
	global_load_dwordx2 v[78:79], v[70:71], off offset:1024
	global_load_dwordx2 v[80:81], v[70:71], off offset:1536
	global_load_dwordx2 v[82:83], v[70:71], off offset:2048
	global_load_dwordx2 v[84:85], v[70:71], off offset:2560
	global_load_dwordx2 v[124:125], v[70:71], off offset:3072
	v_addc_co_u32_e32 v69, vcc, 0, v73, vcc
	global_load_dwordx2 v[126:127], v[70:71], off offset:3584
	global_load_dwordx2 v[128:129], v[68:69], off
	global_load_dwordx2 v[120:121], v[68:69], off offset:512
	v_add_co_u32_e32 v86, vcc, 0x3a200000, v72
	s_nop 1
	v_addc_co_u32_e32 v87, vcc, 0, v73, vcc
	global_load_dwordx2 v[130:131], v[86:87], off
	global_load_dwordx2 v[132:133], v[86:87], off offset:512
	global_load_dwordx2 v[122:123], v[68:69], off offset:1024
	global_load_dwordx2 v[118:119], v[68:69], off offset:1536
	global_load_dwordx2 v[134:135], v[86:87], off offset:1024
	global_load_dwordx2 v[116:117], v[68:69], off offset:2048
	global_load_dwordx2 v[114:115], v[68:69], off offset:2560
	global_load_dwordx2 v[102:103], v[68:69], off offset:3072
	global_load_dwordx2 v[98:99], v[68:69], off offset:3584
	global_load_dwordx2 v[136:137], v[86:87], off offset:1536
	global_load_dwordx2 v[138:139], v[86:87], off offset:2048
	global_load_dwordx2 v[140:141], v[86:87], off offset:2560
	global_load_dwordx2 v[142:143], v[86:87], off offset:3072
	global_load_dwordx2 v[144:145], v[86:87], off offset:3584
	v_add_co_u32_e32 v72, vcc, 0x3a201000, v72
	s_nop 1
	v_addc_co_u32_e32 v73, vcc, 0, v73, vcc
	global_load_dwordx2 v[146:147], v[72:73], off
	global_load_dwordx2 v[148:149], v[72:73], off offset:512
	global_load_dwordx2 v[198:199], v[72:73], off offset:1024
	global_load_dwordx2 v[200:201], v[72:73], off offset:1536
	global_load_dwordx2 v[204:205], v[72:73], off offset:2048
	global_load_dwordx2 v[206:207], v[72:73], off offset:2560
	global_load_dwordx2 v[208:209], v[72:73], off offset:3072
	global_load_dwordx2 v[218:219], v[72:73], off offset:3584
	s_waitcnt vmcnt(22)
	v_lshlrev_b32_e32 v110, 16, v74
	v_lshlrev_b32_e32 v94, 16, v80
	v_lshlrev_b32_e32 v72, 16, v120
	v_and_b32_e32 v73, 0xffff0000, v120
	v_and_b32_e32 v95, 0xffff0000, v80
	v_lshlrev_b32_e32 v96, 16, v81
	v_and_b32_e32 v97, 0xffff0000, v81
	v_lshlrev_b32_e32 v80, 16, v127
	v_and_b32_e32 v81, 0xffff0000, v127
	v_lshlrev_b32_e32 v100, 16, v78
	v_and_b32_e32 v101, 0xffff0000, v78
	v_lshlrev_b32_e32 v106, 16, v79
	v_and_b32_e32 v107, 0xffff0000, v79
	v_lshlrev_b32_e32 v78, 16, v126
	v_and_b32_e32 v79, 0xffff0000, v126
	v_lshlrev_b32_e32 v108, 16, v76
	v_and_b32_e32 v109, 0xffff0000, v76
	v_lshlrev_b32_e32 v104, 16, v77
	v_and_b32_e32 v105, 0xffff0000, v77
	v_lshlrev_b32_e32 v86, 16, v84
	v_and_b32_e32 v87, 0xffff0000, v84
	v_lshlrev_b32_e32 v88, 16, v85
	v_and_b32_e32 v89, 0xffff0000, v85
	v_lshlrev_b32_e32 v84, 16, v125
	v_and_b32_e32 v85, 0xffff0000, v125
	v_lshlrev_b32_e32 v76, 16, v129
	v_and_b32_e32 v77, 0xffff0000, v129
	v_and_b32_e32 v111, 0xffff0000, v74
	v_lshlrev_b32_e32 v112, 16, v75
	v_and_b32_e32 v113, 0xffff0000, v75
	v_lshlrev_b32_e32 v90, 16, v82
	v_and_b32_e32 v91, 0xffff0000, v82
	v_lshlrev_b32_e32 v92, 16, v83
	v_and_b32_e32 v93, 0xffff0000, v83
	v_lshlrev_b32_e32 v82, 16, v124
	v_and_b32_e32 v83, 0xffff0000, v124
	v_lshlrev_b32_e32 v74, 16, v128
	v_and_b32_e32 v75, 0xffff0000, v128
	s_waitcnt vmcnt(21)
	v_and_b32_e32 v197, 0xffff0000, v130
	v_and_b32_e32 v195, 0xffff0000, v131
	v_lshlrev_b32_e32 v196, 16, v130
	v_lshlrev_b32_e32 v194, 16, v131
	v_mul_f32_e32 v0, v197, v197
	v_mul_f32_e32 v67, v195, v195
	v_fmac_f32_e32 v0, v196, v196
	v_fmac_f32_e32 v67, v194, v194
	s_waitcnt vmcnt(20)
	v_and_b32_e32 v193, 0xffff0000, v132
	v_and_b32_e32 v191, 0xffff0000, v133
	v_add_f32_e32 v0, v0, v67
	v_lshlrev_b32_e32 v192, 16, v132
	v_lshlrev_b32_e32 v190, 16, v133
	v_mul_f32_e32 v67, v193, v193
	v_mul_f32_e32 v120, v191, v191
	v_fmac_f32_e32 v67, v192, v192
	v_fmac_f32_e32 v120, v190, v190
	v_add_f32_e32 v67, v67, v120
	s_waitcnt vmcnt(17)
	v_and_b32_e32 v189, 0xffff0000, v134
	v_and_b32_e32 v187, 0xffff0000, v135
	v_add_f32_e32 v0, v0, v67
	v_lshlrev_b32_e32 v188, 16, v134
	v_lshlrev_b32_e32 v186, 16, v135
	v_mul_f32_e32 v67, v189, v189
	v_mul_f32_e32 v120, v187, v187
	v_fmac_f32_e32 v67, v188, v188
	v_fmac_f32_e32 v120, v186, v186
	v_add_f32_e32 v67, v67, v120
	s_waitcnt vmcnt(12)
	v_and_b32_e32 v185, 0xffff0000, v136
	v_and_b32_e32 v183, 0xffff0000, v137
	v_add_f32_e32 v0, v0, v67
	v_lshlrev_b32_e32 v184, 16, v136
	v_lshlrev_b32_e32 v182, 16, v137
	v_mul_f32_e32 v67, v185, v185
	v_mul_f32_e32 v120, v183, v183
	v_fmac_f32_e32 v67, v184, v184
	v_fmac_f32_e32 v120, v182, v182
	v_add_f32_e32 v67, v67, v120
	s_waitcnt vmcnt(11)
	v_and_b32_e32 v181, 0xffff0000, v138
	v_and_b32_e32 v169, 0xffff0000, v139
	v_add_f32_e32 v0, v0, v67
	v_lshlrev_b32_e32 v180, 16, v138
	v_lshlrev_b32_e32 v168, 16, v139
	v_mul_f32_e32 v67, v181, v181
	v_mul_f32_e32 v120, v169, v169
	v_fmac_f32_e32 v67, v180, v180
	v_fmac_f32_e32 v120, v168, v168
	v_add_f32_e32 v67, v67, v120
	s_waitcnt vmcnt(10)
	v_and_b32_e32 v167, 0xffff0000, v140
	v_and_b32_e32 v165, 0xffff0000, v141
	v_add_f32_e32 v0, v0, v67
	v_lshlrev_b32_e32 v166, 16, v140
	v_lshlrev_b32_e32 v164, 16, v141
	v_mul_f32_e32 v67, v167, v167
	v_mul_f32_e32 v120, v165, v165
	v_fmac_f32_e32 v67, v166, v166
	v_fmac_f32_e32 v120, v164, v164
	v_add_f32_e32 v67, v67, v120
	s_waitcnt vmcnt(9)
	v_and_b32_e32 v163, 0xffff0000, v142
	v_and_b32_e32 v161, 0xffff0000, v143
	v_add_f32_e32 v0, v0, v67
	v_lshlrev_b32_e32 v162, 16, v142
	v_lshlrev_b32_e32 v160, 16, v143
	v_mul_f32_e32 v67, v163, v163
	v_mul_f32_e32 v120, v161, v161
	v_fmac_f32_e32 v67, v162, v162
	v_fmac_f32_e32 v120, v160, v160
	v_add_f32_e32 v67, v67, v120
	s_waitcnt vmcnt(8)
	v_and_b32_e32 v159, 0xffff0000, v144
	v_and_b32_e32 v157, 0xffff0000, v145
	v_add_f32_e32 v0, v0, v67
	v_lshlrev_b32_e32 v158, 16, v144
	v_lshlrev_b32_e32 v156, 16, v145
	v_mul_f32_e32 v67, v159, v159
	v_mul_f32_e32 v120, v157, v157
	v_fmac_f32_e32 v67, v158, v158
	v_fmac_f32_e32 v120, v156, v156
	v_add_f32_e32 v67, v67, v120
	s_waitcnt vmcnt(7)
	v_and_b32_e32 v155, 0xffff0000, v146
	v_and_b32_e32 v127, 0xffff0000, v147
	v_add_f32_e32 v0, v0, v67
	v_lshlrev_b32_e32 v154, 16, v146
	v_lshlrev_b32_e32 v126, 16, v147
	v_mul_f32_e32 v67, v155, v155
	v_mul_f32_e32 v120, v127, v127
	v_fmac_f32_e32 v67, v154, v154
	v_fmac_f32_e32 v120, v126, v126
	v_add_f32_e32 v67, v67, v120
	s_waitcnt vmcnt(6)
	v_and_b32_e32 v153, 0xffff0000, v148
	v_and_b32_e32 v131, 0xffff0000, v149
	v_add_f32_e32 v0, v0, v67
	v_lshlrev_b32_e32 v152, 16, v148
	v_lshlrev_b32_e32 v130, 16, v149
	v_mul_f32_e32 v67, v153, v153
	v_mul_f32_e32 v120, v131, v131
	v_fmac_f32_e32 v67, v152, v152
	v_fmac_f32_e32 v120, v130, v130
	v_add_f32_e32 v67, v67, v120
	s_waitcnt vmcnt(5)
	v_and_b32_e32 v151, 0xffff0000, v198
	v_and_b32_e32 v149, 0xffff0000, v199
	v_add_f32_e32 v0, v0, v67
	v_lshlrev_b32_e32 v150, 16, v198
	v_lshlrev_b32_e32 v148, 16, v199
	v_mul_f32_e32 v67, v151, v151
	v_mul_f32_e32 v120, v149, v149
	v_fmac_f32_e32 v67, v150, v150
	v_fmac_f32_e32 v120, v148, v148
	v_add_f32_e32 v67, v67, v120
	s_waitcnt vmcnt(4)
	v_and_b32_e32 v147, 0xffff0000, v200
	v_and_b32_e32 v145, 0xffff0000, v201
	v_add_f32_e32 v0, v0, v67
	v_lshlrev_b32_e32 v146, 16, v200
	v_lshlrev_b32_e32 v144, 16, v201
	v_mul_f32_e32 v67, v147, v147
	v_mul_f32_e32 v120, v145, v145
	v_fmac_f32_e32 v67, v146, v146
	v_fmac_f32_e32 v120, v144, v144
	v_add_f32_e32 v67, v67, v120
	s_waitcnt vmcnt(3)
	v_and_b32_e32 v143, 0xffff0000, v204
	v_and_b32_e32 v141, 0xffff0000, v205
	v_add_f32_e32 v0, v0, v67
	v_lshlrev_b32_e32 v142, 16, v204
	v_lshlrev_b32_e32 v140, 16, v205
	v_mul_f32_e32 v67, v143, v143
	v_mul_f32_e32 v120, v141, v141
	v_fmac_f32_e32 v67, v142, v142
	v_fmac_f32_e32 v120, v140, v140
	v_add_f32_e32 v67, v67, v120
	s_waitcnt vmcnt(2)
	v_and_b32_e32 v139, 0xffff0000, v206
	v_and_b32_e32 v137, 0xffff0000, v207
	v_add_f32_e32 v0, v0, v67
	v_lshlrev_b32_e32 v138, 16, v206
	v_lshlrev_b32_e32 v136, 16, v207
	v_mul_f32_e32 v67, v139, v139
	v_mul_f32_e32 v120, v137, v137
	v_fmac_f32_e32 v67, v138, v138
	v_fmac_f32_e32 v120, v136, v136
	v_add_f32_e32 v67, v67, v120
	s_waitcnt vmcnt(1)
	v_and_b32_e32 v129, 0xffff0000, v208
	v_and_b32_e32 v125, 0xffff0000, v209
	v_add_f32_e32 v0, v0, v67
	v_lshlrev_b32_e32 v128, 16, v208
	v_lshlrev_b32_e32 v124, 16, v209
	v_mul_f32_e32 v67, v129, v129
	v_mul_f32_e32 v120, v125, v125
	v_fmac_f32_e32 v67, v128, v128
	v_fmac_f32_e32 v120, v124, v124
	v_add_f32_e32 v67, v67, v120
	s_waitcnt vmcnt(0)
	v_and_b32_e32 v135, 0xffff0000, v218
	v_and_b32_e32 v133, 0xffff0000, v219
	v_add_f32_e32 v0, v0, v67
	v_lshlrev_b32_e32 v134, 16, v218
	v_lshlrev_b32_e32 v132, 16, v219
	v_mul_f32_e32 v67, v135, v135
	v_mul_f32_e32 v120, v133, v133
	v_fmac_f32_e32 v67, v134, v134
	v_fmac_f32_e32 v120, v132, v132
	v_add_f32_e32 v67, v67, v120
	v_add_f32_e32 v0, v0, v67
	v_lshlrev_b32_e32 v198, 16, v102
	v_and_b32_e32 v199, 0xffff0000, v102
	v_lshlrev_b32_e32 v228, 16, v103
	v_and_b32_e32 v229, 0xffff0000, v103
	s_waitcnt lgkmcnt(0)
	v_add_f32_dpp v0, v0, v0 quad_perm:[1,0,3,2] row_mask:0xf bank_mask:0xf
	v_lshlrev_b32_e32 v200, 16, v98
	v_and_b32_e32 v201, 0xffff0000, v98
	v_lshlrev_b32_e32 v230, 16, v99
	v_and_b32_e32 v231, 0xffff0000, v99
	s_waitcnt lgkmcnt(0)
	v_add_f32_dpp v0, v0, v0 quad_perm:[2,3,0,1] row_mask:0xf bank_mask:0xf
	v_lshlrev_b32_e32 v224, 16, v114
	v_and_b32_e32 v225, 0xffff0000, v114
	v_lshlrev_b32_e32 v226, 16, v115
	v_and_b32_e32 v227, 0xffff0000, v115
	s_waitcnt lgkmcnt(0)
	v_add_f32_dpp v0, v0, v0 row_half_mirror row_mask:0xf bank_mask:0xf
	v_lshlrev_b32_e32 v204, 16, v121
	v_and_b32_e32 v205, 0xffff0000, v121
	v_lshlrev_b32_e32 v220, 16, v116
	v_and_b32_e32 v221, 0xffff0000, v116
	s_waitcnt lgkmcnt(0)
	v_add_f32_dpp v0, v0, v0 row_mirror row_mask:0xf bank_mask:0xf
	ds_swizzle_b32 v67, v0 offset:swizzle(SWAP,16)
	v_lshlrev_b32_e32 v222, 16, v117
	v_and_b32_e32 v223, 0xffff0000, v117
	v_lshlrev_b32_e32 v206, 16, v122
	v_and_b32_e32 v207, 0xffff0000, v122
	s_waitcnt lgkmcnt(0)
	v_add_f32_e32 v0, v0, v67
	v_lshlrev_b32_e32 v208, 16, v123
	v_readlane_b32 s1, v0, 32
	v_readlane_b32 s0, v0, 0
	v_and_b32_e32 v209, 0xffff0000, v123
	v_mov_b32_e32 v0, s1
	v_add_f32_e32 v0, s0, v0
	v_fmamk_f32 v0, v0, 0x39800000, v211
	v_mul_f32_e32 v67, 0x4f800000, v0
	v_cmp_gt_f32_e32 vcc, s94, v0
	v_lshlrev_b32_e32 v218, 16, v118
	v_and_b32_e32 v219, 0xffff0000, v118
	v_cndmask_b32_e32 v0, v0, v67, vcc
	v_sqrt_f32_e32 v67, v0
	v_lshlrev_b32_e32 v118, 16, v119
	v_and_b32_e32 v119, 0xffff0000, v119
	v_add_u32_e32 v102, -1, v67
	v_fma_f32 v103, -v102, v67, v0
	v_cmp_ge_f32_e64 s[0:1], 0, v103
	v_add_u32_e32 v103, 1, v67
	s_nop 0
	v_cndmask_b32_e64 v102, v67, v102, s[0:1]
	v_fma_f32 v67, -v103, v67, v0
	v_cmp_lt_f32_e64 s[0:1], 0, v67
	s_nop 1
	v_cndmask_b32_e64 v67, v102, v103, s[0:1]
	v_mul_f32_e32 v102, 0x37800000, v67
	v_cndmask_b32_e32 v67, v67, v102, vcc
	v_cmp_class_f32_e32 vcc, v0, v212
	s_nop 1
	v_cndmask_b32_e32 v0, v67, v0, vcc
	v_div_scale_f32 v67, s[0:1], v0, v0, 1.0
	v_rcp_f32_e32 v102, v67
	s_nop 0
	v_fma_f32 v98, -v67, v102, 1.0
	v_fmac_f32_e32 v102, v98, v102
	v_div_scale_f32 v98, vcc, 1.0, v0, 1.0
	v_mul_f32_e32 v99, v98, v102
	v_fma_f32 v103, -v67, v99, v98
	v_fmac_f32_e32 v99, v103, v102
	v_fma_f32 v67, -v67, v99, v98
	v_div_fmas_f32 v67, v67, v102, v99
	v_div_fixup_f32 v0, v67, v0, 1.0
	v_pk_mul_f32 v[98:99], v[0:1], v[194:195] op_sel_hi:[0,1]
	v_pk_fma_f32 v[98:99], v[4:5], v[98:99], v[112:113]
	v_pk_mul_f32 v[112:113], v[0:1], v[190:191] op_sel_hi:[0,1]
	v_pk_fma_f32 v[104:105], v[8:9], v[112:113], v[104:105]
	v_pk_mul_f32 v[112:113], v[0:1], v[186:187] op_sel_hi:[0,1]
	v_pk_mul_f32 v[102:103], v[0:1], v[196:197] op_sel_hi:[0,1]
	v_pk_fma_f32 v[106:107], v[12:13], v[112:113], v[106:107]
	v_pk_mul_f32 v[112:113], v[0:1], v[182:183] op_sel_hi:[0,1]
	v_pk_fma_f32 v[102:103], v[2:3], v[102:103], v[110:111]
	v_pk_mul_f32 v[110:111], v[0:1], v[192:193] op_sel_hi:[0,1]
	v_pk_fma_f32 v[96:97], v[16:17], v[112:113], v[96:97]
	v_pk_mul_f32 v[112:113], v[0:1], v[168:169] op_sel_hi:[0,1]
	v_pk_fma_f32 v[108:109], v[6:7], v[110:111], v[108:109]
	v_pk_mul_f32 v[110:111], v[0:1], v[188:189] op_sel_hi:[0,1]
	v_pk_fma_f32 v[92:93], v[20:21], v[112:113], v[92:93]
	v_pk_mul_f32 v[112:113], v[0:1], v[164:165] op_sel_hi:[0,1]
	v_pk_fma_f32 v[100:101], v[10:11], v[110:111], v[100:101]
	v_pk_mul_f32 v[110:111], v[0:1], v[184:185] op_sel_hi:[0,1]
	v_pk_fma_f32 v[88:89], v[24:25], v[112:113], v[88:89]
	v_pk_mul_f32 v[112:113], v[0:1], v[162:163] op_sel_hi:[0,1]
	v_pk_fma_f32 v[94:95], v[14:15], v[110:111], v[94:95]
	v_pk_mul_f32 v[110:111], v[0:1], v[180:181] op_sel_hi:[0,1]
	v_pk_fma_f32 v[114:115], v[26:27], v[112:113], v[82:83]
	v_pk_mul_f32 v[112:113], v[0:1], v[136:137] op_sel_hi:[0,1]
	v_cvt_pk_bf16_f32 v136, v102, v103
	v_cvt_pk_bf16_f32 v137, v98, v99
	v_pk_fma_f32 v[90:91], v[18:19], v[110:111], v[90:91]
	v_pk_mul_f32 v[110:111], v[0:1], v[166:167] op_sel_hi:[0,1]
	global_store_dwordx2 v[70:71], v[136:137], off
	v_cvt_pk_bf16_f32 v136, v108, v109
	v_cvt_pk_bf16_f32 v137, v104, v105
	v_pk_fma_f32 v[86:87], v[22:23], v[110:111], v[86:87]
	v_pk_mul_f32 v[110:111], v[0:1], v[160:161] op_sel_hi:[0,1]
	global_store_dwordx2 v[70:71], v[136:137], off offset:512
	v_cvt_pk_bf16_f32 v136, v100, v101
	v_cvt_pk_bf16_f32 v137, v106, v107
	v_pk_fma_f32 v[110:111], v[28:29], v[110:111], v[84:85]
	v_pk_mul_f32 v[82:83], v[0:1], v[158:159] op_sel_hi:[0,1]
	v_pk_mul_f32 v[84:85], v[0:1], v[156:157] op_sel_hi:[0,1]
	global_store_dwordx2 v[70:71], v[136:137], off offset:1024
	v_cvt_pk_bf16_f32 v136, v94, v95
	v_cvt_pk_bf16_f32 v137, v96, v97
	v_pk_fma_f32 v[116:117], v[32:33], v[84:85], v[80:81]
	v_pk_fma_f32 v[120:121], v[30:31], v[82:83], v[78:79]
	v_pk_mul_f32 v[78:79], v[0:1], v[154:155] op_sel_hi:[0,1]
	v_pk_mul_f32 v[80:81], v[0:1], v[126:127] op_sel_hi:[0,1]
	global_store_dwordx2 v[70:71], v[136:137], off offset:1536
	v_cvt_pk_bf16_f32 v136, v90, v91
	v_cvt_pk_bf16_f32 v137, v92, v93
	v_pk_fma_f32 v[122:123], v[44:45], v[80:81], v[76:77]
	v_pk_fma_f32 v[126:127], v[42:43], v[78:79], v[74:75]
	v_pk_mul_f32 v[76:77], v[0:1], v[152:153] op_sel_hi:[0,1]
	v_pk_mul_f32 v[78:79], v[0:1], v[144:145] op_sel_hi:[0,1]
	global_store_dwordx2 v[70:71], v[136:137], off offset:2048
	v_cvt_pk_bf16_f32 v136, v86, v87
	v_cvt_pk_bf16_f32 v137, v88, v89
	v_pk_mul_f32 v[74:75], v[0:1], v[130:131] op_sel_hi:[0,1]
	v_pk_fma_f32 v[130:131], v[34:35], v[76:77], v[72:73]
	v_pk_mul_f32 v[76:77], v[0:1], v[150:151] op_sel_hi:[0,1]
	v_pk_mul_f32 v[72:73], v[0:1], v[148:149] op_sel_hi:[0,1]
	v_pk_mul_f32 v[80:81], v[0:1], v[146:147] op_sel_hi:[0,1]
	v_pk_fma_f32 v[78:79], v[48:49], v[78:79], v[118:119]
	v_pk_mul_f32 v[84:85], v[0:1], v[142:143] op_sel_hi:[0,1]
	v_pk_mul_f32 v[82:83], v[0:1], v[140:141] op_sel_hi:[0,1]
	v_pk_mul_f32 v[118:119], v[0:1], v[138:139] op_sel_hi:[0,1]
	v_pk_mul_f32 v[128:129], v[0:1], v[128:129] op_sel_hi:[0,1]
	v_pk_mul_f32 v[124:125], v[0:1], v[124:125] op_sel_hi:[0,1]
	v_pk_mul_f32 v[134:135], v[0:1], v[134:135] op_sel_hi:[0,1]
	v_pk_mul_f32 v[132:133], v[0:1], v[132:133] op_sel_hi:[0,1]
	global_store_dwordx2 v[70:71], v[136:137], off offset:2560
	v_cvt_pk_bf16_f32 v136, v114, v115
	v_cvt_pk_bf16_f32 v137, v110, v111
	v_mul_f32_e32 v0, v103, v103
	v_mul_f32_e32 v67, v99, v99
	global_store_dwordx2 v[70:71], v[136:137], off offset:3072
	v_cvt_pk_bf16_f32 v136, v120, v121
	v_cvt_pk_bf16_f32 v137, v116, v117
	global_store_dwordx2 v[70:71], v[136:137], off offset:3584
	v_cvt_pk_bf16_f32 v70, v126, v127
	v_cvt_pk_bf16_f32 v71, v122, v123
	v_fmac_f32_e32 v0, v102, v102
	v_fmac_f32_e32 v67, v98, v98
	global_store_dwordx2 v[68:69], v[70:71], off
	v_add_f32_e32 v0, v0, v67
	v_mul_f32_e32 v67, v109, v109
	v_mul_f32_e32 v71, v105, v105
	v_fmac_f32_e32 v67, v108, v108
	v_fmac_f32_e32 v71, v104, v104
	v_add_f32_e32 v67, v67, v71
	v_add_f32_e32 v0, v0, v67
	v_mul_f32_e32 v67, v101, v101
	v_mul_f32_e32 v71, v107, v107
	v_fmac_f32_e32 v67, v100, v100
	v_fmac_f32_e32 v71, v106, v106
	v_add_f32_e32 v67, v67, v71
	v_add_f32_e32 v0, v67, v0
	v_mul_f32_e32 v67, v95, v95
	v_mul_f32_e32 v71, v97, v97
	v_fmac_f32_e32 v67, v94, v94
	v_fmac_f32_e32 v71, v96, v96
	v_add_f32_e32 v67, v67, v71
	v_add_f32_e32 v0, v67, v0
	v_mul_f32_e32 v67, v91, v91
	v_mul_f32_e32 v71, v93, v93
	v_fmac_f32_e32 v67, v90, v90
	v_fmac_f32_e32 v71, v92, v92
	v_add_f32_e32 v67, v67, v71
	v_add_f32_e32 v0, v67, v0
	v_mul_f32_e32 v67, v87, v87
	v_mul_f32_e32 v71, v89, v89
	v_fmac_f32_e32 v67, v86, v86
	v_fmac_f32_e32 v71, v88, v88
	v_add_f32_e32 v67, v67, v71
	v_add_f32_e32 v0, v67, v0
	v_mul_f32_e32 v67, v115, v115
	v_mul_f32_e32 v71, v111, v111
	v_fmac_f32_e32 v67, v114, v114
	v_fmac_f32_e32 v71, v110, v110
	v_add_f32_e32 v67, v67, v71
	v_add_f32_e32 v0, v67, v0
	v_mul_f32_e32 v67, v121, v121
	v_mul_f32_e32 v71, v117, v117
	v_fmac_f32_e32 v67, v120, v120
	v_fmac_f32_e32 v71, v116, v116
	v_add_f32_e32 v67, v67, v71
	v_add_f32_e32 v0, v67, v0
	v_mul_f32_e32 v67, v127, v127
	v_mul_f32_e32 v71, v123, v123
	v_fmac_f32_e32 v67, v126, v126
	v_fmac_f32_e32 v71, v122, v122
	v_pk_fma_f32 v[74:75], v[36:37], v[74:75], v[204:205]
	v_add_f32_e32 v67, v67, v71
	v_add_f32_e32 v0, v67, v0
	v_mul_f32_e32 v67, v131, v131
	v_mul_f32_e32 v71, v75, v75
	v_fmac_f32_e32 v67, v130, v130
	v_fmac_f32_e32 v71, v74, v74
	v_pk_fma_f32 v[72:73], v[40:41], v[72:73], v[208:209]
	v_pk_fma_f32 v[76:77], v[38:39], v[76:77], v[206:207]
	v_add_f32_e32 v67, v67, v71
	v_add_f32_e32 v0, v67, v0
	v_mul_f32_e32 v67, v77, v77
	v_mul_f32_e32 v71, v73, v73
	v_fmac_f32_e32 v67, v76, v76
	v_fmac_f32_e32 v71, v72, v72
	v_pk_fma_f32 v[80:81], v[46:47], v[80:81], v[218:219]
	v_add_f32_e32 v67, v67, v71
	v_add_f32_e32 v0, v67, v0
	v_mul_f32_e32 v67, v81, v81
	v_mul_f32_e32 v71, v79, v79
	v_fmac_f32_e32 v67, v80, v80
	v_fmac_f32_e32 v71, v78, v78
	v_pk_fma_f32 v[82:83], v[52:53], v[82:83], v[222:223]
	v_pk_fma_f32 v[84:85], v[50:51], v[84:85], v[220:221]
	v_add_f32_e32 v67, v67, v71
	v_add_f32_e32 v0, v67, v0
	v_mul_f32_e32 v67, v85, v85
	v_mul_f32_e32 v71, v83, v83
	v_fmac_f32_e32 v67, v84, v84
	v_fmac_f32_e32 v71, v82, v82
	v_pk_fma_f32 v[112:113], v[56:57], v[112:113], v[226:227]
	v_pk_fma_f32 v[118:119], v[54:55], v[118:119], v[224:225]
	v_add_f32_e32 v67, v67, v71
	v_add_f32_e32 v0, v67, v0
	v_mul_f32_e32 v67, v119, v119
	v_mul_f32_e32 v71, v113, v113
	v_fmac_f32_e32 v67, v118, v118
	v_fmac_f32_e32 v71, v112, v112
	v_pk_fma_f32 v[124:125], v[60:61], v[124:125], v[228:229]
	v_pk_fma_f32 v[128:129], v[58:59], v[128:129], v[198:199]
	v_add_f32_e32 v67, v67, v71
	v_add_f32_e32 v0, v67, v0
	v_mul_f32_e32 v67, v129, v129
	v_mul_f32_e32 v71, v125, v125
	v_fmac_f32_e32 v67, v128, v128
	v_fmac_f32_e32 v71, v124, v124
	v_pk_fma_f32 v[132:133], v[64:65], v[132:133], v[230:231]
	v_pk_fma_f32 v[134:135], v[62:63], v[134:135], v[200:201]
	v_add_f32_e32 v67, v67, v71
	v_add_f32_e32 v0, v67, v0
	v_mul_f32_e32 v67, v135, v135
	v_mul_f32_e32 v71, v133, v133
	v_fmac_f32_e32 v67, v134, v134
	v_fmac_f32_e32 v71, v132, v132
	v_add_f32_e32 v67, v67, v71
	v_add_f32_e32 v0, v67, v0
	v_cvt_pk_bf16_f32 v70, v130, v131
	v_cvt_pk_bf16_f32 v71, v74, v75
	global_store_dwordx2 v[68:69], v[70:71], off offset:512
	v_cvt_pk_bf16_f32 v70, v76, v77
	s_waitcnt lgkmcnt(0)
	v_add_f32_dpp v0, v0, v0 quad_perm:[1,0,3,2] row_mask:0xf bank_mask:0xf
	v_cvt_pk_bf16_f32 v71, v72, v73
	global_store_dwordx2 v[68:69], v[70:71], off offset:1024
	v_cvt_pk_bf16_f32 v70, v80, v81
	v_cvt_pk_bf16_f32 v71, v78, v79
	s_waitcnt lgkmcnt(0)
	v_add_f32_dpp v0, v0, v0 quad_perm:[2,3,0,1] row_mask:0xf bank_mask:0xf
	global_store_dwordx2 v[68:69], v[70:71], off offset:1536
	v_cvt_pk_bf16_f32 v70, v84, v85
	v_cvt_pk_bf16_f32 v71, v82, v83
	global_store_dwordx2 v[68:69], v[70:71], off offset:2048
	s_waitcnt lgkmcnt(0)
	v_add_f32_dpp v0, v0, v0 row_half_mirror row_mask:0xf bank_mask:0xf
	v_cvt_pk_bf16_f32 v70, v118, v119
	v_cvt_pk_bf16_f32 v71, v112, v113
	global_store_dwordx2 v[68:69], v[70:71], off offset:2560
	v_cvt_pk_bf16_f32 v70, v128, v129
	s_waitcnt lgkmcnt(0)
	v_add_f32_dpp v0, v0, v0 row_mirror row_mask:0xf bank_mask:0xf
	ds_swizzle_b32 v67, v0 offset:swizzle(SWAP,16)
	v_cvt_pk_bf16_f32 v71, v124, v125
	v_cmp_eq_u32_e32 vcc, 0, v66
	global_store_dwordx2 v[68:69], v[70:71], off offset:3072
	v_cvt_pk_bf16_f32 v70, v134, v135
	s_waitcnt lgkmcnt(0)
	v_add_f32_e32 v0, v0, v67
	v_cvt_pk_bf16_f32 v71, v132, v133
	global_store_dwordx2 v[68:69], v[70:71], off offset:3584
	v_readlane_b32 s0, v0, 0
	v_readlane_b32 s1, v0, 32
	s_and_saveexec_b64 s[4:5], vcc
	s_cbranch_execz .LBB0_804
	v_mov_b32_e32 v0, s1
	v_add_f32_e32 v0, s0, v0
	v_fmamk_f32 v0, v0, 0x39800000, v211
	v_mul_f32_e32 v66, 0x4f800000, v0
	v_cmp_gt_f32_e32 vcc, s94, v0
	v_readlane_b32 s16, v252, 0
	v_readlane_b32 s18, v252, 2
	v_cndmask_b32_e32 v0, v0, v66, vcc
	v_sqrt_f32_e32 v66, v0
	v_readlane_b32 s19, v252, 3
	v_readlane_b32 s17, v252, 1
	v_add_u32_e32 v67, -1, v66
	v_fma_f32 v69, -v67, v66, v0
	v_add_u32_e32 v68, 1, v66
	v_cmp_ge_f32_e64 s[0:1], 0, v69
	s_nop 1
	v_cndmask_b32_e64 v67, v66, v67, s[0:1]
	v_fma_f32 v66, -v68, v66, v0
	v_cmp_lt_f32_e64 s[0:1], 0, v66
	s_nop 1
	v_cndmask_b32_e64 v66, v67, v68, s[0:1]
	v_mul_f32_e32 v67, 0x37800000, v66
	v_cndmask_b32_e32 v66, v66, v67, vcc
	v_cmp_class_f32_e32 vcc, v0, v212
	s_nop 1
	v_cndmask_b32_e32 v0, v66, v0, vcc
	v_div_scale_f32 v66, s[0:1], v0, v0, 1.0
	v_rcp_f32_e32 v67, v66
	s_add_u32 s0, s18, s7
	s_addc_u32 s1, s19, s8
	v_fma_f32 v68, -v66, v67, 1.0
	v_fmac_f32_e32 v67, v68, v67
	v_div_scale_f32 v68, vcc, 1.0, v0, 1.0
	v_mul_f32_e32 v69, v68, v67
	v_fma_f32 v70, -v66, v69, v68
	v_fmac_f32_e32 v69, v70, v67
	v_fma_f32 v66, -v66, v69, v68
	v_div_fmas_f32 v66, v66, v67, v69
	v_div_fixup_f32 v0, v66, v0, 1.0
	global_store_dword v1, v0, s[0:1]
	s_branch .LBB0_804

.LBB0_1241:
	v_readlane_b32 s16, v252, 0
	v_readlane_b32 s18, v252, 2
	v_mov_b32_e32 v68, v204
	v_readlane_b32 s19, v252, 3
	s_add_u32 s0, s18, s2
	s_addc_u32 s1, s19, s3
	v_ashrrev_i32_e32 v69, 31, v68
	v_lshl_add_u64 v[74:75], v[68:69], 3, s[0:1]
	v_add_co_u32_e32 v72, vcc, 0x44700000, v74
	v_readlane_b32 s17, v252, 1
	s_nop 0
	v_addc_co_u32_e32 v73, vcc, 0, v75, vcc
	v_add_co_u32_e32 v70, vcc, 0x44701000, v74
	global_load_dwordx2 v[76:77], v[72:73], off
	global_load_dwordx2 v[78:79], v[72:73], off offset:512
	global_load_dwordx2 v[80:81], v[72:73], off offset:1024
	global_load_dwordx2 v[82:83], v[72:73], off offset:1536
	global_load_dwordx2 v[84:85], v[72:73], off offset:2048
	global_load_dwordx2 v[86:87], v[72:73], off offset:2560
	global_load_dwordx2 v[126:127], v[72:73], off offset:3072
	v_addc_co_u32_e32 v71, vcc, 0, v75, vcc
	global_load_dwordx2 v[128:129], v[72:73], off offset:3584
	global_load_dwordx2 v[130:131], v[70:71], off
	global_load_dwordx2 v[122:123], v[70:71], off offset:512
	v_add_co_u32_e32 v88, vcc, 0x3a200000, v74
	s_nop 1
	v_addc_co_u32_e32 v89, vcc, 0, v75, vcc
	global_load_dwordx2 v[132:133], v[88:89], off
	global_load_dwordx2 v[134:135], v[88:89], off offset:512
	global_load_dwordx2 v[124:125], v[70:71], off offset:1024
	global_load_dwordx2 v[120:121], v[70:71], off offset:1536
	global_load_dwordx2 v[136:137], v[88:89], off offset:1024
	global_load_dwordx2 v[118:119], v[70:71], off offset:2048
	global_load_dwordx2 v[116:117], v[70:71], off offset:2560
	global_load_dwordx2 v[104:105], v[70:71], off offset:3072
	global_load_dwordx2 v[100:101], v[70:71], off offset:3584
	global_load_dwordx2 v[138:139], v[88:89], off offset:1536
	global_load_dwordx2 v[140:141], v[88:89], off offset:2048
	global_load_dwordx2 v[142:143], v[88:89], off offset:2560
	global_load_dwordx2 v[144:145], v[88:89], off offset:3072
	global_load_dwordx2 v[146:147], v[88:89], off offset:3584
	v_add_co_u32_e32 v74, vcc, 0x3a201000, v74
	s_nop 1
	v_addc_co_u32_e32 v75, vcc, 0, v75, vcc
	global_load_dwordx2 v[148:149], v[74:75], off
	global_load_dwordx2 v[150:151], v[74:75], off offset:512
	global_load_dwordx2 v[200:201], v[74:75], off offset:1024
	global_load_dwordx2 v[202:203], v[74:75], off offset:1536
	global_load_dwordx2 v[206:207], v[74:75], off offset:2048
	global_load_dwordx2 v[208:209], v[74:75], off offset:2560
	global_load_dwordx2 v[218:219], v[74:75], off offset:3072
	global_load_dwordx2 v[220:221], v[74:75], off offset:3584
	s_waitcnt vmcnt(22)
	v_lshlrev_b32_e32 v112, 16, v76
	v_lshlrev_b32_e32 v96, 16, v82
	v_lshlrev_b32_e32 v74, 16, v122
	v_and_b32_e32 v75, 0xffff0000, v122
	v_and_b32_e32 v97, 0xffff0000, v82
	v_lshlrev_b32_e32 v98, 16, v83
	v_and_b32_e32 v99, 0xffff0000, v83
	v_lshlrev_b32_e32 v82, 16, v129
	v_and_b32_e32 v83, 0xffff0000, v129
	v_lshlrev_b32_e32 v102, 16, v80
	v_and_b32_e32 v103, 0xffff0000, v80
	v_lshlrev_b32_e32 v108, 16, v81
	v_and_b32_e32 v109, 0xffff0000, v81
	v_lshlrev_b32_e32 v80, 16, v128
	v_and_b32_e32 v81, 0xffff0000, v128
	v_lshlrev_b32_e32 v110, 16, v78
	v_and_b32_e32 v111, 0xffff0000, v78
	v_lshlrev_b32_e32 v106, 16, v79
	v_and_b32_e32 v107, 0xffff0000, v79
	v_lshlrev_b32_e32 v88, 16, v86
	v_and_b32_e32 v89, 0xffff0000, v86
	v_lshlrev_b32_e32 v90, 16, v87
	v_and_b32_e32 v91, 0xffff0000, v87
	v_lshlrev_b32_e32 v86, 16, v127
	v_and_b32_e32 v87, 0xffff0000, v127
	v_lshlrev_b32_e32 v78, 16, v131
	v_and_b32_e32 v79, 0xffff0000, v131
	v_and_b32_e32 v113, 0xffff0000, v76
	v_lshlrev_b32_e32 v114, 16, v77
	v_and_b32_e32 v115, 0xffff0000, v77
	v_lshlrev_b32_e32 v92, 16, v84
	v_and_b32_e32 v93, 0xffff0000, v84
	v_lshlrev_b32_e32 v94, 16, v85
	v_and_b32_e32 v95, 0xffff0000, v85
	v_lshlrev_b32_e32 v84, 16, v126
	v_and_b32_e32 v85, 0xffff0000, v126
	v_lshlrev_b32_e32 v76, 16, v130
	v_and_b32_e32 v77, 0xffff0000, v130
	s_waitcnt vmcnt(21)
	v_and_b32_e32 v199, 0xffff0000, v132
	v_and_b32_e32 v197, 0xffff0000, v133
	v_lshlrev_b32_e32 v198, 16, v132
	v_lshlrev_b32_e32 v196, 16, v133
	v_mul_f32_e32 v0, v199, v199
	v_mul_f32_e32 v69, v197, v197
	v_fmac_f32_e32 v0, v198, v198
	v_fmac_f32_e32 v69, v196, v196
	s_waitcnt vmcnt(20)
	v_and_b32_e32 v195, 0xffff0000, v134
	v_and_b32_e32 v193, 0xffff0000, v135
	v_add_f32_e32 v0, v0, v69
	v_lshlrev_b32_e32 v194, 16, v134
	v_lshlrev_b32_e32 v192, 16, v135
	v_mul_f32_e32 v69, v195, v195
	v_mul_f32_e32 v122, v193, v193
	v_fmac_f32_e32 v69, v194, v194
	v_fmac_f32_e32 v122, v192, v192
	v_add_f32_e32 v69, v69, v122
	s_waitcnt vmcnt(17)
	v_and_b32_e32 v191, 0xffff0000, v136
	v_and_b32_e32 v189, 0xffff0000, v137
	v_add_f32_e32 v0, v0, v69
	v_lshlrev_b32_e32 v190, 16, v136
	v_lshlrev_b32_e32 v188, 16, v137
	v_mul_f32_e32 v69, v191, v191
	v_mul_f32_e32 v122, v189, v189
	v_fmac_f32_e32 v69, v190, v190
	v_fmac_f32_e32 v122, v188, v188
	v_add_f32_e32 v69, v69, v122
	s_waitcnt vmcnt(12)
	v_and_b32_e32 v187, 0xffff0000, v138
	v_and_b32_e32 v185, 0xffff0000, v139
	v_add_f32_e32 v0, v0, v69
	v_lshlrev_b32_e32 v186, 16, v138
	v_lshlrev_b32_e32 v184, 16, v139
	v_mul_f32_e32 v69, v187, v187
	v_mul_f32_e32 v122, v185, v185
	v_fmac_f32_e32 v69, v186, v186
	v_fmac_f32_e32 v122, v184, v184
	v_add_f32_e32 v69, v69, v122
	s_waitcnt vmcnt(11)
	v_and_b32_e32 v183, 0xffff0000, v140
	v_and_b32_e32 v181, 0xffff0000, v141
	v_add_f32_e32 v0, v0, v69
	v_lshlrev_b32_e32 v182, 16, v140
	v_lshlrev_b32_e32 v180, 16, v141
	v_mul_f32_e32 v69, v183, v183
	v_mul_f32_e32 v122, v181, v181
	v_fmac_f32_e32 v69, v182, v182
	v_fmac_f32_e32 v122, v180, v180
	v_add_f32_e32 v69, v69, v122
	s_waitcnt vmcnt(10)
	v_and_b32_e32 v169, 0xffff0000, v142
	v_and_b32_e32 v167, 0xffff0000, v143
	v_add_f32_e32 v0, v0, v69
	v_lshlrev_b32_e32 v168, 16, v142
	v_lshlrev_b32_e32 v166, 16, v143
	v_mul_f32_e32 v69, v169, v169
	v_mul_f32_e32 v122, v167, v167
	v_fmac_f32_e32 v69, v168, v168
	v_fmac_f32_e32 v122, v166, v166
	v_add_f32_e32 v69, v69, v122
	s_waitcnt vmcnt(9)
	v_and_b32_e32 v165, 0xffff0000, v144
	v_and_b32_e32 v163, 0xffff0000, v145
	v_add_f32_e32 v0, v0, v69
	v_lshlrev_b32_e32 v164, 16, v144
	v_lshlrev_b32_e32 v162, 16, v145
	v_mul_f32_e32 v69, v165, v165
	v_mul_f32_e32 v122, v163, v163
	v_fmac_f32_e32 v69, v164, v164
	v_fmac_f32_e32 v122, v162, v162
	v_add_f32_e32 v69, v69, v122
	s_waitcnt vmcnt(8)
	v_and_b32_e32 v161, 0xffff0000, v146
	v_and_b32_e32 v159, 0xffff0000, v147
	v_add_f32_e32 v0, v0, v69
	v_lshlrev_b32_e32 v160, 16, v146
	v_lshlrev_b32_e32 v158, 16, v147
	v_mul_f32_e32 v69, v161, v161
	v_mul_f32_e32 v122, v159, v159
	v_fmac_f32_e32 v69, v160, v160
	v_fmac_f32_e32 v122, v158, v158
	v_add_f32_e32 v69, v69, v122
	s_waitcnt vmcnt(7)
	v_and_b32_e32 v157, 0xffff0000, v148
	v_and_b32_e32 v129, 0xffff0000, v149
	v_add_f32_e32 v0, v0, v69
	v_lshlrev_b32_e32 v156, 16, v148
	v_lshlrev_b32_e32 v128, 16, v149
	v_mul_f32_e32 v69, v157, v157
	v_mul_f32_e32 v122, v129, v129
	v_fmac_f32_e32 v69, v156, v156
	v_fmac_f32_e32 v122, v128, v128
	v_add_f32_e32 v69, v69, v122
	s_waitcnt vmcnt(6)
	v_and_b32_e32 v155, 0xffff0000, v150
	v_and_b32_e32 v133, 0xffff0000, v151
	v_add_f32_e32 v0, v0, v69
	v_lshlrev_b32_e32 v154, 16, v150
	v_lshlrev_b32_e32 v132, 16, v151
	v_mul_f32_e32 v69, v155, v155
	v_mul_f32_e32 v122, v133, v133
	v_fmac_f32_e32 v69, v154, v154
	v_fmac_f32_e32 v122, v132, v132
	v_add_f32_e32 v69, v69, v122
	s_waitcnt vmcnt(5)
	v_and_b32_e32 v153, 0xffff0000, v200
	v_and_b32_e32 v151, 0xffff0000, v201
	v_add_f32_e32 v0, v0, v69
	v_lshlrev_b32_e32 v152, 16, v200
	v_lshlrev_b32_e32 v150, 16, v201
	v_mul_f32_e32 v69, v153, v153
	v_mul_f32_e32 v122, v151, v151
	v_fmac_f32_e32 v69, v152, v152
	v_fmac_f32_e32 v122, v150, v150
	v_add_f32_e32 v69, v69, v122
	s_waitcnt vmcnt(4)
	v_and_b32_e32 v149, 0xffff0000, v202
	v_and_b32_e32 v147, 0xffff0000, v203
	v_add_f32_e32 v0, v0, v69
	v_lshlrev_b32_e32 v148, 16, v202
	v_lshlrev_b32_e32 v146, 16, v203
	v_mul_f32_e32 v69, v149, v149
	v_mul_f32_e32 v122, v147, v147
	v_fmac_f32_e32 v69, v148, v148
	v_fmac_f32_e32 v122, v146, v146
	v_add_f32_e32 v69, v69, v122
	s_waitcnt vmcnt(3)
	v_and_b32_e32 v145, 0xffff0000, v206
	v_and_b32_e32 v143, 0xffff0000, v207
	v_add_f32_e32 v0, v0, v69
	v_lshlrev_b32_e32 v144, 16, v206
	v_lshlrev_b32_e32 v142, 16, v207
	v_mul_f32_e32 v69, v145, v145
	v_mul_f32_e32 v122, v143, v143
	v_fmac_f32_e32 v69, v144, v144
	v_fmac_f32_e32 v122, v142, v142
	v_add_f32_e32 v69, v69, v122
	s_waitcnt vmcnt(2)
	v_and_b32_e32 v141, 0xffff0000, v208
	v_and_b32_e32 v139, 0xffff0000, v209
	v_add_f32_e32 v0, v0, v69
	v_lshlrev_b32_e32 v140, 16, v208
	v_lshlrev_b32_e32 v138, 16, v209
	v_mul_f32_e32 v69, v141, v141
	v_mul_f32_e32 v122, v139, v139
	v_fmac_f32_e32 v69, v140, v140
	v_fmac_f32_e32 v122, v138, v138
	v_add_f32_e32 v69, v69, v122
	s_waitcnt vmcnt(1)
	v_and_b32_e32 v131, 0xffff0000, v218
	v_and_b32_e32 v127, 0xffff0000, v219
	v_add_f32_e32 v0, v0, v69
	v_lshlrev_b32_e32 v130, 16, v218
	v_lshlrev_b32_e32 v126, 16, v219
	v_mul_f32_e32 v69, v131, v131
	v_mul_f32_e32 v122, v127, v127
	v_fmac_f32_e32 v69, v130, v130
	v_fmac_f32_e32 v122, v126, v126
	v_add_f32_e32 v69, v69, v122
	s_waitcnt vmcnt(0)
	v_and_b32_e32 v137, 0xffff0000, v220
	v_and_b32_e32 v135, 0xffff0000, v221
	v_add_f32_e32 v0, v0, v69
	v_lshlrev_b32_e32 v136, 16, v220
	v_lshlrev_b32_e32 v134, 16, v221
	v_mul_f32_e32 v69, v137, v137
	v_mul_f32_e32 v122, v135, v135
	v_fmac_f32_e32 v69, v136, v136
	v_fmac_f32_e32 v122, v134, v134
	v_add_f32_e32 v69, v69, v122
	v_add_f32_e32 v0, v0, v69
	v_lshlrev_b32_e32 v200, 16, v104
	v_and_b32_e32 v201, 0xffff0000, v104
	v_lshlrev_b32_e32 v230, 16, v105
	v_and_b32_e32 v231, 0xffff0000, v105
	s_waitcnt lgkmcnt(0)
	v_add_f32_dpp v0, v0, v0 quad_perm:[1,0,3,2] row_mask:0xf bank_mask:0xf
	v_lshlrev_b32_e32 v202, 16, v100
	v_and_b32_e32 v203, 0xffff0000, v100
	v_lshlrev_b32_e32 v232, 16, v101
	v_and_b32_e32 v233, 0xffff0000, v101
	s_waitcnt lgkmcnt(0)
	v_add_f32_dpp v0, v0, v0 quad_perm:[2,3,0,1] row_mask:0xf bank_mask:0xf
	v_lshlrev_b32_e32 v226, 16, v116
	v_and_b32_e32 v227, 0xffff0000, v116
	v_lshlrev_b32_e32 v228, 16, v117
	v_and_b32_e32 v229, 0xffff0000, v117
	s_waitcnt lgkmcnt(0)
	v_add_f32_dpp v0, v0, v0 row_half_mirror row_mask:0xf bank_mask:0xf
	v_lshlrev_b32_e32 v206, 16, v123
	v_and_b32_e32 v207, 0xffff0000, v123
	v_lshlrev_b32_e32 v222, 16, v118
	v_and_b32_e32 v223, 0xffff0000, v118
	s_waitcnt lgkmcnt(0)
	v_add_f32_dpp v0, v0, v0 row_mirror row_mask:0xf bank_mask:0xf
	ds_swizzle_b32 v69, v0 offset:swizzle(SWAP,16)
	v_lshlrev_b32_e32 v224, 16, v119
	v_and_b32_e32 v225, 0xffff0000, v119
	v_lshlrev_b32_e32 v208, 16, v124
	v_and_b32_e32 v209, 0xffff0000, v124
	s_waitcnt lgkmcnt(0)
	v_add_f32_e32 v0, v0, v69
	v_lshlrev_b32_e32 v218, 16, v125
	v_readlane_b32 s1, v0, 32
	v_readlane_b32 s0, v0, 0
	v_and_b32_e32 v219, 0xffff0000, v125
	v_mov_b32_e32 v0, s1
	v_add_f32_e32 v0, s0, v0
	v_fmamk_f32 v0, v0, 0x39800000, v211
	v_mul_f32_e32 v69, 0x4f800000, v0
	v_cmp_gt_f32_e32 vcc, s94, v0
	v_lshlrev_b32_e32 v220, 16, v120
	v_and_b32_e32 v221, 0xffff0000, v120
	v_cndmask_b32_e32 v0, v0, v69, vcc
	v_sqrt_f32_e32 v69, v0
	v_lshlrev_b32_e32 v120, 16, v121
	v_and_b32_e32 v121, 0xffff0000, v121
	v_add_u32_e32 v104, -1, v69
	v_fma_f32 v105, -v104, v69, v0
	v_cmp_ge_f32_e64 s[0:1], 0, v105
	v_add_u32_e32 v105, 1, v69
	s_nop 0
	v_cndmask_b32_e64 v104, v69, v104, s[0:1]
	v_fma_f32 v69, -v105, v69, v0
	v_cmp_lt_f32_e64 s[0:1], 0, v69
	s_nop 1
	v_cndmask_b32_e64 v69, v104, v105, s[0:1]
	v_mul_f32_e32 v104, 0x37800000, v69
	v_cndmask_b32_e32 v69, v69, v104, vcc
	v_cmp_class_f32_e32 vcc, v0, v212
	s_nop 1
	v_cndmask_b32_e32 v0, v69, v0, vcc
	v_div_scale_f32 v69, s[0:1], v0, v0, 1.0
	v_rcp_f32_e32 v104, v69
	s_nop 0
	v_fma_f32 v100, -v69, v104, 1.0
	v_fmac_f32_e32 v104, v100, v104
	v_div_scale_f32 v100, vcc, 1.0, v0, 1.0
	v_mul_f32_e32 v101, v100, v104
	v_fma_f32 v105, -v69, v101, v100
	v_fmac_f32_e32 v101, v105, v104
	v_fma_f32 v69, -v69, v101, v100
	v_div_fmas_f32 v69, v69, v104, v101
	v_div_fixup_f32 v0, v69, v0, 1.0
	v_pk_mul_f32 v[100:101], v[0:1], v[196:197] op_sel_hi:[0,1]
	v_pk_fma_f32 v[100:101], v[4:5], v[100:101], v[114:115]
	v_pk_mul_f32 v[114:115], v[0:1], v[192:193] op_sel_hi:[0,1]
	v_pk_fma_f32 v[106:107], v[8:9], v[114:115], v[106:107]
	v_pk_mul_f32 v[114:115], v[0:1], v[188:189] op_sel_hi:[0,1]
	v_pk_mul_f32 v[104:105], v[0:1], v[198:199] op_sel_hi:[0,1]
	v_pk_fma_f32 v[108:109], v[12:13], v[114:115], v[108:109]
	v_pk_mul_f32 v[114:115], v[0:1], v[184:185] op_sel_hi:[0,1]
	v_pk_fma_f32 v[104:105], v[2:3], v[104:105], v[112:113]
	v_pk_mul_f32 v[112:113], v[0:1], v[194:195] op_sel_hi:[0,1]
	v_pk_fma_f32 v[98:99], v[16:17], v[114:115], v[98:99]
	v_pk_mul_f32 v[114:115], v[0:1], v[180:181] op_sel_hi:[0,1]
	v_pk_fma_f32 v[110:111], v[6:7], v[112:113], v[110:111]
	v_pk_mul_f32 v[112:113], v[0:1], v[190:191] op_sel_hi:[0,1]
	v_pk_fma_f32 v[94:95], v[20:21], v[114:115], v[94:95]
	v_pk_mul_f32 v[114:115], v[0:1], v[166:167] op_sel_hi:[0,1]
	v_pk_fma_f32 v[102:103], v[10:11], v[112:113], v[102:103]
	v_pk_mul_f32 v[112:113], v[0:1], v[186:187] op_sel_hi:[0,1]
	v_pk_fma_f32 v[90:91], v[24:25], v[114:115], v[90:91]
	v_pk_mul_f32 v[114:115], v[0:1], v[164:165] op_sel_hi:[0,1]
	v_pk_fma_f32 v[96:97], v[14:15], v[112:113], v[96:97]
	v_pk_mul_f32 v[112:113], v[0:1], v[182:183] op_sel_hi:[0,1]
	v_pk_fma_f32 v[116:117], v[26:27], v[114:115], v[84:85]
	v_pk_mul_f32 v[114:115], v[0:1], v[138:139] op_sel_hi:[0,1]
	v_cvt_pk_bf16_f32 v138, v104, v105
	v_cvt_pk_bf16_f32 v139, v100, v101
	v_pk_fma_f32 v[92:93], v[18:19], v[112:113], v[92:93]
	v_pk_mul_f32 v[112:113], v[0:1], v[168:169] op_sel_hi:[0,1]
	global_store_dwordx2 v[72:73], v[138:139], off
	v_cvt_pk_bf16_f32 v138, v110, v111
	v_cvt_pk_bf16_f32 v139, v106, v107
	v_pk_fma_f32 v[88:89], v[22:23], v[112:113], v[88:89]
	v_pk_mul_f32 v[112:113], v[0:1], v[162:163] op_sel_hi:[0,1]
	global_store_dwordx2 v[72:73], v[138:139], off offset:512
	v_cvt_pk_bf16_f32 v138, v102, v103
	v_cvt_pk_bf16_f32 v139, v108, v109
	v_pk_fma_f32 v[112:113], v[28:29], v[112:113], v[86:87]
	v_pk_mul_f32 v[84:85], v[0:1], v[160:161] op_sel_hi:[0,1]
	v_pk_mul_f32 v[86:87], v[0:1], v[158:159] op_sel_hi:[0,1]
	global_store_dwordx2 v[72:73], v[138:139], off offset:1024
	v_cvt_pk_bf16_f32 v138, v96, v97
	v_cvt_pk_bf16_f32 v139, v98, v99
	v_pk_fma_f32 v[118:119], v[32:33], v[86:87], v[82:83]
	v_pk_fma_f32 v[122:123], v[30:31], v[84:85], v[80:81]
	v_pk_mul_f32 v[80:81], v[0:1], v[156:157] op_sel_hi:[0,1]
	v_pk_mul_f32 v[82:83], v[0:1], v[128:129] op_sel_hi:[0,1]
	global_store_dwordx2 v[72:73], v[138:139], off offset:1536
	v_cvt_pk_bf16_f32 v138, v92, v93
	v_cvt_pk_bf16_f32 v139, v94, v95
	v_pk_fma_f32 v[124:125], v[44:45], v[82:83], v[78:79]
	v_pk_fma_f32 v[128:129], v[42:43], v[80:81], v[76:77]
	v_pk_mul_f32 v[78:79], v[0:1], v[154:155] op_sel_hi:[0,1]
	v_pk_mul_f32 v[80:81], v[0:1], v[146:147] op_sel_hi:[0,1]
	global_store_dwordx2 v[72:73], v[138:139], off offset:2048
	v_cvt_pk_bf16_f32 v138, v88, v89
	v_cvt_pk_bf16_f32 v139, v90, v91
	v_pk_mul_f32 v[76:77], v[0:1], v[132:133] op_sel_hi:[0,1]
	v_pk_fma_f32 v[132:133], v[34:35], v[78:79], v[74:75]
	v_pk_mul_f32 v[78:79], v[0:1], v[152:153] op_sel_hi:[0,1]
	v_pk_mul_f32 v[74:75], v[0:1], v[150:151] op_sel_hi:[0,1]
	v_pk_mul_f32 v[82:83], v[0:1], v[148:149] op_sel_hi:[0,1]
	v_pk_fma_f32 v[80:81], v[48:49], v[80:81], v[120:121]
	v_pk_mul_f32 v[86:87], v[0:1], v[144:145] op_sel_hi:[0,1]
	v_pk_mul_f32 v[84:85], v[0:1], v[142:143] op_sel_hi:[0,1]
	v_pk_mul_f32 v[120:121], v[0:1], v[140:141] op_sel_hi:[0,1]
	v_pk_mul_f32 v[130:131], v[0:1], v[130:131] op_sel_hi:[0,1]
	v_pk_mul_f32 v[126:127], v[0:1], v[126:127] op_sel_hi:[0,1]
	v_pk_mul_f32 v[136:137], v[0:1], v[136:137] op_sel_hi:[0,1]
	v_pk_mul_f32 v[134:135], v[0:1], v[134:135] op_sel_hi:[0,1]
	global_store_dwordx2 v[72:73], v[138:139], off offset:2560
	v_cvt_pk_bf16_f32 v138, v116, v117
	v_cvt_pk_bf16_f32 v139, v112, v113
	v_mul_f32_e32 v0, v105, v105
	v_mul_f32_e32 v69, v101, v101
	global_store_dwordx2 v[72:73], v[138:139], off offset:3072
	v_cvt_pk_bf16_f32 v138, v122, v123
	v_cvt_pk_bf16_f32 v139, v118, v119
	global_store_dwordx2 v[72:73], v[138:139], off offset:3584
	v_cvt_pk_bf16_f32 v72, v128, v129
	v_cvt_pk_bf16_f32 v73, v124, v125
	v_fmac_f32_e32 v0, v104, v104
	v_fmac_f32_e32 v69, v100, v100
	global_store_dwordx2 v[70:71], v[72:73], off
	v_add_f32_e32 v0, v0, v69
	v_mul_f32_e32 v69, v111, v111
	v_mul_f32_e32 v73, v107, v107
	v_fmac_f32_e32 v69, v110, v110
	v_fmac_f32_e32 v73, v106, v106
	v_add_f32_e32 v69, v69, v73
	v_add_f32_e32 v0, v0, v69
	v_mul_f32_e32 v69, v103, v103
	v_mul_f32_e32 v73, v109, v109
	v_fmac_f32_e32 v69, v102, v102
	v_fmac_f32_e32 v73, v108, v108
	v_add_f32_e32 v69, v69, v73
	v_add_f32_e32 v0, v69, v0
	v_mul_f32_e32 v69, v97, v97
	v_mul_f32_e32 v73, v99, v99
	v_fmac_f32_e32 v69, v96, v96
	v_fmac_f32_e32 v73, v98, v98
	v_add_f32_e32 v69, v69, v73
	v_add_f32_e32 v0, v69, v0
	v_mul_f32_e32 v69, v93, v93
	v_mul_f32_e32 v73, v95, v95
	v_fmac_f32_e32 v69, v92, v92
	v_fmac_f32_e32 v73, v94, v94
	v_add_f32_e32 v69, v69, v73
	v_add_f32_e32 v0, v69, v0
	v_mul_f32_e32 v69, v89, v89
	v_mul_f32_e32 v73, v91, v91
	v_fmac_f32_e32 v69, v88, v88
	v_fmac_f32_e32 v73, v90, v90
	v_add_f32_e32 v69, v69, v73
	v_add_f32_e32 v0, v69, v0
	v_mul_f32_e32 v69, v117, v117
	v_mul_f32_e32 v73, v113, v113
	v_fmac_f32_e32 v69, v116, v116
	v_fmac_f32_e32 v73, v112, v112
	v_add_f32_e32 v69, v69, v73
	v_add_f32_e32 v0, v69, v0
	v_mul_f32_e32 v69, v123, v123
	v_mul_f32_e32 v73, v119, v119
	v_fmac_f32_e32 v69, v122, v122
	v_fmac_f32_e32 v73, v118, v118
	v_add_f32_e32 v69, v69, v73
	v_add_f32_e32 v0, v69, v0
	v_mul_f32_e32 v69, v129, v129
	v_mul_f32_e32 v73, v125, v125
	v_fmac_f32_e32 v69, v128, v128
	v_fmac_f32_e32 v73, v124, v124
	v_pk_fma_f32 v[76:77], v[36:37], v[76:77], v[206:207]
	v_add_f32_e32 v69, v69, v73
	v_add_f32_e32 v0, v69, v0
	v_mul_f32_e32 v69, v133, v133
	v_mul_f32_e32 v73, v77, v77
	v_fmac_f32_e32 v69, v132, v132
	v_fmac_f32_e32 v73, v76, v76
	v_pk_fma_f32 v[74:75], v[40:41], v[74:75], v[218:219]
	v_pk_fma_f32 v[78:79], v[38:39], v[78:79], v[208:209]
	v_add_f32_e32 v69, v69, v73
	v_add_f32_e32 v0, v69, v0
	v_mul_f32_e32 v69, v79, v79
	v_mul_f32_e32 v73, v75, v75
	v_fmac_f32_e32 v69, v78, v78
	v_fmac_f32_e32 v73, v74, v74
	v_pk_fma_f32 v[82:83], v[46:47], v[82:83], v[220:221]
	v_add_f32_e32 v69, v69, v73
	v_add_f32_e32 v0, v69, v0
	v_mul_f32_e32 v69, v83, v83
	v_mul_f32_e32 v73, v81, v81
	v_fmac_f32_e32 v69, v82, v82
	v_fmac_f32_e32 v73, v80, v80
	v_pk_fma_f32 v[84:85], v[52:53], v[84:85], v[224:225]
	v_pk_fma_f32 v[86:87], v[50:51], v[86:87], v[222:223]
	v_add_f32_e32 v69, v69, v73
	v_add_f32_e32 v0, v69, v0
	v_mul_f32_e32 v69, v87, v87
	v_mul_f32_e32 v73, v85, v85
	v_fmac_f32_e32 v69, v86, v86
	v_fmac_f32_e32 v73, v84, v84
	v_pk_fma_f32 v[114:115], v[56:57], v[114:115], v[228:229]
	v_pk_fma_f32 v[120:121], v[54:55], v[120:121], v[226:227]
	v_add_f32_e32 v69, v69, v73
	v_add_f32_e32 v0, v69, v0
	v_mul_f32_e32 v69, v121, v121
	v_mul_f32_e32 v73, v115, v115
	v_fmac_f32_e32 v69, v120, v120
	v_fmac_f32_e32 v73, v114, v114
	v_pk_fma_f32 v[126:127], v[60:61], v[126:127], v[230:231]
	v_pk_fma_f32 v[130:131], v[58:59], v[130:131], v[200:201]
	v_add_f32_e32 v69, v69, v73
	v_add_f32_e32 v0, v69, v0
	v_mul_f32_e32 v69, v131, v131
	v_mul_f32_e32 v73, v127, v127
	v_fmac_f32_e32 v69, v130, v130
	v_fmac_f32_e32 v73, v126, v126
	v_pk_fma_f32 v[134:135], v[64:65], v[134:135], v[232:233]
	v_pk_fma_f32 v[136:137], v[62:63], v[136:137], v[202:203]
	v_add_f32_e32 v69, v69, v73
	v_add_f32_e32 v0, v69, v0
	v_mul_f32_e32 v69, v137, v137
	v_mul_f32_e32 v73, v135, v135
	v_fmac_f32_e32 v69, v136, v136
	v_fmac_f32_e32 v73, v134, v134
	v_add_f32_e32 v69, v69, v73
	v_add_f32_e32 v0, v69, v0
	v_cvt_pk_bf16_f32 v72, v132, v133
	v_cvt_pk_bf16_f32 v73, v76, v77
	global_store_dwordx2 v[70:71], v[72:73], off offset:512
	v_cvt_pk_bf16_f32 v72, v78, v79
	s_waitcnt lgkmcnt(0)
	v_add_f32_dpp v0, v0, v0 quad_perm:[1,0,3,2] row_mask:0xf bank_mask:0xf
	v_cvt_pk_bf16_f32 v73, v74, v75
	global_store_dwordx2 v[70:71], v[72:73], off offset:1024
	v_cvt_pk_bf16_f32 v72, v82, v83
	v_cvt_pk_bf16_f32 v73, v80, v81
	s_waitcnt lgkmcnt(0)
	v_add_f32_dpp v0, v0, v0 quad_perm:[2,3,0,1] row_mask:0xf bank_mask:0xf
	global_store_dwordx2 v[70:71], v[72:73], off offset:1536
	v_cvt_pk_bf16_f32 v72, v86, v87
	v_cvt_pk_bf16_f32 v73, v84, v85
	global_store_dwordx2 v[70:71], v[72:73], off offset:2048
	s_waitcnt lgkmcnt(0)
	v_add_f32_dpp v0, v0, v0 row_half_mirror row_mask:0xf bank_mask:0xf
	v_cvt_pk_bf16_f32 v72, v120, v121
	v_cvt_pk_bf16_f32 v73, v114, v115
	global_store_dwordx2 v[70:71], v[72:73], off offset:2560
	v_cvt_pk_bf16_f32 v72, v130, v131
	s_waitcnt lgkmcnt(0)
	v_add_f32_dpp v0, v0, v0 row_mirror row_mask:0xf bank_mask:0xf
	ds_swizzle_b32 v69, v0 offset:swizzle(SWAP,16)
	v_cvt_pk_bf16_f32 v73, v126, v127
	v_cmp_eq_u32_e32 vcc, 0, v68
	global_store_dwordx2 v[70:71], v[72:73], off offset:3072
	v_cvt_pk_bf16_f32 v72, v136, v137
	s_waitcnt lgkmcnt(0)
	v_add_f32_e32 v0, v0, v69
	v_cvt_pk_bf16_f32 v73, v134, v135
	global_store_dwordx2 v[70:71], v[72:73], off offset:3584
	v_readlane_b32 s0, v0, 0
	v_readlane_b32 s1, v0, 32
	s_and_saveexec_b64 s[4:5], vcc
	s_cbranch_execz .LBB0_1240
	v_mov_b32_e32 v0, s1
	v_add_f32_e32 v0, s0, v0
	v_fmamk_f32 v0, v0, 0x39800000, v211
	v_mul_f32_e32 v68, 0x4f800000, v0
	v_cmp_gt_f32_e32 vcc, s94, v0
	v_readlane_b32 s16, v252, 0
	v_readlane_b32 s18, v252, 2
	v_cndmask_b32_e32 v0, v0, v68, vcc
	v_sqrt_f32_e32 v68, v0
	v_readlane_b32 s19, v252, 3
	v_readlane_b32 s17, v252, 1
	v_add_u32_e32 v69, -1, v68
	v_fma_f32 v71, -v69, v68, v0
	v_add_u32_e32 v70, 1, v68
	v_cmp_ge_f32_e64 s[0:1], 0, v71
	s_nop 1
	v_cndmask_b32_e64 v69, v68, v69, s[0:1]
	v_fma_f32 v68, -v70, v68, v0
	v_cmp_lt_f32_e64 s[0:1], 0, v68
	s_nop 1
	v_cndmask_b32_e64 v68, v69, v70, s[0:1]
	v_mul_f32_e32 v69, 0x37800000, v68
	v_cndmask_b32_e32 v68, v68, v69, vcc
	v_cmp_class_f32_e32 vcc, v0, v212
	s_nop 1
	v_cndmask_b32_e32 v0, v68, v0, vcc
	v_div_scale_f32 v68, s[0:1], v0, v0, 1.0
	v_rcp_f32_e32 v69, v68
	s_add_u32 s0, s18, s8
	s_addc_u32 s1, s19, s9
	v_fma_f32 v70, -v68, v69, 1.0
	v_fmac_f32_e32 v69, v70, v69
	v_div_scale_f32 v70, vcc, 1.0, v0, 1.0
	v_mul_f32_e32 v71, v70, v69
	v_fma_f32 v72, -v68, v71, v70
	v_fmac_f32_e32 v71, v72, v69
	v_fma_f32 v68, -v68, v71, v70
	v_div_fmas_f32 v68, v68, v69, v71
	v_div_fixup_f32 v0, v68, v0, 1.0
	global_store_dword v1, v0, s[0:1]
	s_branch .LBB0_1240
